# barrier leader skips the L2 write-back after phases 3,7,13,19 (all stores write-through)
# speedup vs baseline: 1.0109x; 1.0109x over previous
.LBB0_1042:
	v_cvt_f32_u32_e32 v4, v2
	v_sub_u32_e32 v3, 0, v2
	v_rcp_iflag_f32_e32 v4, v4
	s_nop 0
	v_mul_f32_e32 v4, 0x4f7ffffe, v4
	v_cvt_u32_f32_e32 v4, v4
	v_mul_lo_u32 v1, v3, v4
	v_mul_hi_u32 v1, v4, v1
	v_add_u32_e32 v1, v4, v1
	s_waitcnt vmcnt(0)
	v_mov_b32_e32 v5, v165
	v_mul_hi_u32 v1, v5, v1
	v_mul_lo_u32 v3, v1, v2
	v_sub_u32_e32 v3, v5, v3
	v_add_u32_e32 v4, 1, v1
	v_cmp_ge_u32_e32 vcc, v3, v2
	s_nop 1
	v_cndmask_b32_e32 v1, v1, v4, vcc
	v_sub_u32_e32 v4, v3, v2
	v_cndmask_b32_e32 v3, v3, v4, vcc
	v_add_u32_e32 v4, 1, v1
	v_cmp_ge_u32_e32 vcc, v3, v2
	v_add_u32_e32 v3, 1, v5
	s_nop 0
	v_cndmask_b32_e32 v1, v1, v4, vcc
	v_mul_lo_u32 v4, v2, v1
	v_add_u32_e32 v2, v4, v2
	v_cmp_ne_u32_e32 vcc, v3, v2
	s_waitcnt lgkmcnt(0)
	v_mad_u32_u24 v5, v1, v0, v0
	s_add_u32 s10, s90, 0x494e400
	s_addc_u32 s11, s91, 0
	s_cbranch_vccnz .Lgb_poll
	s_mov_b32 s2, 0x82088
	s_bitcmp1_b32 s2, s86
	s_cbranch_scc1 .Lgb_nowb
	buffer_wbl2 sc1
	s_waitcnt vmcnt(0)
